# P4: defer first-chunk zeroing selects of prefetched C/n/m to next loop top so prefetch loads are not waited right after issue
# speedup vs baseline: 1.0028x; 1.0028x over previous
.LBB0_569:
	v_and_b32_e32 v47, 63, v128
	v_cmp_eq_u32_e64 s[4:5], 0, v47
	v_cmp_gt_u32_e64 s[6:7], 2, v47
	v_cmp_gt_u32_e64 s[8:9], 4, v47
	v_cmp_gt_u32_e64 s[10:11], 8, v47
	v_cmp_gt_u32_e64 s[12:13], 16, v47
	v_cmp_gt_u32_e64 s[14:15], 32, v47
	s_add_i32 s42, 16, 0x17c00
	v_lshlrev_b32_e32 v47, 2, v47
	s_add_i32 s18, 16, 0x17d00
	s_add_i32 s43, 16, 0x17e00
	s_add_i32 s54, 16, 0x17f00
	s_add_i32 s62, 16, 0x18000
	s_add_i32 s64, 16, 0x18200
	s_add_i32 s65, 16, 0x18300
	v_lshrrev_b32_e32 v45, 7, v45
	v_add_u32_e32 v112, s42, v47
	v_add_u32_e32 v113, s18, v47
	v_add_u32_e32 v114, s43, v47
	v_add_u32_e32 v115, s54, v47
	v_add_u32_e32 v116, s62, v47
	v_add_u32_e32 v117, s64, v47
	v_add_u32_e32 v118, s65, v47
	v_lshrrev_b32_e32 v47, 7, v128
	v_xor_b32_e32 v45, v45, v128
	v_lshl_add_u32 v52, v48, 1, 16
	v_lshl_or_b32 v53, v47, 4, v110
	v_and_b32_e32 v63, 7, v129
	v_mul_u32_u24_e32 v65, 0x88, v129
	v_mul_u32_u24_e32 v48, 0x48, v48
	v_lshlrev_b32_e32 v45, 3, v45
	v_lshlrev_b32_e32 v54, 2, v53
	v_and_b32_e32 v56, 48, v128
	v_lshrrev_b32_e32 v58, 3, v128
	s_add_i32 s68, 16, 0x18100
	v_lshl_add_u32 v127, v65, 1, v52
	v_xor_b32_e32 v65, v47, v128
	v_lshlrev_b32_e32 v48, 1, v48
	v_and_or_b32 v45, v45, 56, v63
	s_add_i32 s19, 16, 0x18400
	v_add_u32_e32 v120, s18, v54
	v_add_u32_e32 v57, 16, v56
	s_movk_i32 s18, 0x110
	s_movk_i32 s20, 0x90
	v_and_b32_e32 v59, 7, v128
	v_mul_u32_u24_e32 v60, 0x110, v58
	v_lshl_add_u32 v125, v58, 2, s68
	v_or_b32_e32 v58, v50, v110
	v_lshlrev_b32_e32 v65, 3, v65
	v_add_u32_e32 v66, 16, v48
	v_lshlrev_b32_e32 v45, 1, v45
	v_lshl_add_u32 v119, v128, 2, s19
	v_mad_u32_u24 v121, v53, s18, v57
	v_lshlrev_b32_e32 v61, 5, v59
	v_lshl_add_u32 v124, v59, 6, s19
	v_cmp_eq_u32_e64 s[18:19], 0, v59
	v_mad_u32_u24 v59, v58, s20, 16
	v_and_or_b32 v65, v65, 56, v63
	v_add3_u32 v133, 16, v45, v48
	v_add_u32_e32 v134, v66, v45
	v_mul_u32_u24_e32 v45, 0x110, v129
	s_mov_b32 s20, 0xd000
	v_lshlrev_b32_e32 v49, 1, v49
	v_lshlrev_b32_e32 v65, 1, v65
	v_add3_u32 v135, v52, v45, s20
	v_add_u32_e32 v45, 0x600, v128
	v_bfe_u32 v51, v128, 4, 2
	v_and_b32_e32 v49, 2, v49
	v_add3_u32 v130, 16, v65, v48
	v_add_u32_e32 v131, v66, v65
	v_mul_u32_u24_e32 v65, 0x88, v111
	v_lshrrev_b32_e32 v45, 4, v45
	v_lshlrev_b32_e32 v55, 2, v51
	v_lshl_add_u32 v132, v65, 1, v52
	v_mul_u32_u24_e32 v65, 0x110, v45
	v_lshlrev_b32_e32 v45, 4, v49
	v_or_b32_e32 v48, v45, v55
	v_or_b32_e32 v67, 2, v48
	v_add_u32_e32 v122, s62, v54
	v_mul_u32_u24_e32 v54, 0x90, v53
	s_add_i32 s30, 16, 0x15800
	v_or_b32_e32 v66, v45, v110
	v_cmp_le_u32_e64 s[22:23], v48, v53
	v_lshl_add_u32 v136, v48, 2, s42
	v_cmp_lt_u32_e64 s[24:25], v48, v53
	v_cmp_le_u32_e64 s[26:27], v67, v53
	v_lshl_add_u32 v137, v67, 2, s42
	v_or_b32_e32 v67, 3, v48
	v_lshlrev_b32_e32 v48, 1, v48
	v_or_b32_e32 v45, 16, v45
	v_add3_u32 v139, s30, v54, v48
	v_or_b32_e32 v48, v45, v55
	v_or_b32_e32 v45, v45, v110
	v_mul_u32_u24_e32 v54, 0x110, v45
	v_or_b32_e32 v45, 2, v48
	v_lshlrev_b32_e32 v51, 3, v51
	v_cmp_le_u32_e64 s[38:39], v45, v53
	v_lshl_add_u32 v141, v45, 2, s42
	v_or_b32_e32 v45, 3, v48
	v_add3_u32 v123, 16, v60, v61
	v_bitop3_b32 v60, v50, 56, v110 bitop3:0xc8
	v_cmp_le_u32_e64 s[40:41], v45, v53
	v_lshl_add_u32 v142, v45, 2, s42
	v_bitop3_b32 v45, v58, v51, 56 bitop3:0x6c
	v_lshl_add_u32 v143, v45, 1, v59
	v_bitop3_b32 v45, v51, v60, 32 bitop3:0x36
	v_or_b32_e32 v150, 16, v110
	v_lshl_add_u32 v144, v45, 1, v59
	v_lshlrev_b32_e32 v45, 2, v150
	v_or_b32_e32 v157, 32, v110
	v_add_u32_e32 v151, s43, v45
	v_add_u32_e32 v152, s62, v45
	v_add_u32_e32 v153, s68, v45
	v_add_u32_e32 v154, s54, v45
	v_add_u32_e32 v155, s65, v45
	v_add_u32_e32 v156, s64, v45
	v_lshlrev_b32_e32 v45, 2, v157
	v_or_b32_e32 v164, 48, v110
	v_mov_b32_e32 v89, 0
	v_add_u32_e32 v158, s43, v45
	v_add_u32_e32 v159, s62, v45
	v_add_u32_e32 v160, s68, v45
	v_add_u32_e32 v161, s54, v45
	v_add_u32_e32 v162, s65, v45
	v_add_u32_e32 v163, s64, v45
	v_lshlrev_b32_e32 v45, 2, v164
	v_add_u32_e32 v165, s43, v45
	v_add_u32_e32 v166, s62, v45
	v_add_u32_e32 v167, s68, v45
	v_add_u32_e32 v168, s54, v45
	v_add_u32_e32 v169, s65, v45
	v_add_u32_e32 v170, s64, v45
	v_mov_b32_e32 v45, v89
	v_mov_b32_e32 v88, v84
	v_lshl_add_u64 v[96:97], s[0:1], 0, v[44:45]
	v_mbcnt_lo_u32_b32 v44, -1, 0
	v_add_u32_e32 v62, s30, v56
	v_cmp_le_u32_e64 s[20:21], v49, v47
	v_cmp_lt_u32_e64 s[30:31], v49, v47
	v_cmp_le_u32_e64 s[34:35], v48, v53
	v_lshl_add_u32 v140, v48, 2, s42
	v_cmp_lt_u32_e64 s[36:37], v48, v53
	v_lshl_add_u64 v[48:49], s[74:75], 0, v[88:89]
	v_mov_b32_e32 v47, v89
	v_mbcnt_hi_u32_b32 v44, -1, v44
	v_lshl_add_u64 v[94:95], v[48:49], 0, v[46:47]
	v_and_b32_e32 v46, 64, v44
	v_xor_b32_e32 v45, 16, v44
	v_add_u32_e32 v47, 64, v46
	v_cmp_lt_i32_e32 vcc, v45, v47
	s_movk_i32 s16, 0x80
	v_lshl_add_u32 v61, v58, 7, v59
	v_cndmask_b32_e32 v45, v44, v45, vcc
	v_lshlrev_b32_e32 v84, 2, v45
	v_xor_b32_e32 v45, 32, v44
	v_cmp_lt_i32_e32 vcc, v45, v47
	v_or_b32_e32 v50, v55, v50
	v_lshlrev_b32_e32 v64, 2, v110
	v_cndmask_b32_e32 v45, v44, v45, vcc
	v_lshlrev_b32_e32 v171, 2, v45
	v_add_u32_e32 v45, -1, v44
	v_cmp_lt_i32_e32 vcc, v45, v46
	v_mul_u32_u24_e32 v63, 0x110, v111
	v_mul_u32_u24_e32 v66, 0x110, v66
	v_cndmask_b32_e32 v45, v45, v44, vcc
	v_lshlrev_b32_e32 v172, 2, v45
	v_add_u32_e32 v45, -2, v44
	v_cmp_lt_i32_e32 vcc, v45, v46
	v_cmp_le_u32_e64 s[28:29], v67, v53
	v_mul_u32_u24_e32 v51, 0x90, v110
	v_cndmask_b32_e32 v45, v45, v44, vcc
	v_lshlrev_b32_e32 v173, 2, v45
	v_add_u32_e32 v45, -4, v44
	v_cmp_lt_i32_e32 vcc, v45, v46
	v_mul_u32_u24_e32 v53, 0x110, v110
	v_mov_b32_e32 v77, v89
	v_cndmask_b32_e32 v45, v45, v44, vcc
	v_lshlrev_b32_e32 v174, 2, v45
	v_add_u32_e32 v45, -8, v44
	v_cmp_lt_i32_e32 vcc, v45, v46
	s_mov_b32 s55, 0
	v_cmp_gt_u32_e64 s[16:17], s16, v128
	v_cndmask_b32_e32 v45, v45, v44, vcc
	v_lshlrev_b32_e32 v175, 2, v45
	v_add_u32_e32 v45, -16, v44
	v_cmp_lt_i32_e32 vcc, v45, v46
	v_add_u32_e32 v126, s64, v64
	v_lshl_add_u32 v138, v67, 2, s42
	v_cndmask_b32_e32 v45, v45, v44, vcc
	v_lshlrev_b32_e32 v176, 2, v45
	v_subrev_u32_e32 v45, 32, v44
	v_cmp_lt_i32_e32 vcc, v45, v46
	s_and_b64 s[56:57], s[12:13], s[20:21]
	s_and_b64 s[60:61], s[12:13], s[30:31]
	v_cndmask_b32_e32 v45, v45, v44, vcc
	v_lshlrev_b32_e32 v177, 2, v45
	v_xor_b32_e32 v45, 1, v44
	v_cmp_lt_i32_e32 vcc, v45, v47
	v_add_u32_e32 v145, s43, v64
	v_add_u32_e32 v146, s62, v64
	v_cndmask_b32_e32 v45, v44, v45, vcc
	v_lshlrev_b32_e32 v178, 2, v45
	v_xor_b32_e32 v45, 2, v44
	v_cmp_lt_i32_e32 vcc, v45, v47
	v_add_u32_e32 v147, s68, v64
	v_add_u32_e32 v148, s54, v64
	v_cndmask_b32_e32 v45, v44, v45, vcc
	v_lshlrev_b32_e32 v179, 2, v45
	v_xor_b32_e32 v45, 4, v44
	v_cmp_lt_i32_e32 vcc, v45, v47
	v_add_u32_e32 v149, s65, v64
	v_lshl_add_u64 v[92:93], s[78:79], 0, v[76:77]
	v_cndmask_b32_e32 v44, v44, v45, vcc
	v_lshlrev_b32_e32 v180, 2, v44
	s_lshl_b32 s68, s84, 3
	s_lshl_b32 s69, s33, 6
	s_lshl_b32 s70, s84, 6
	v_add_u32_e32 v181, v52, v63
	v_add_u32_e32 v182, v52, v65
	s_movk_i32 s71, 0x3800
	s_movk_i32 s72, 0x1000
	s_movk_i32 s73, 0x2000
	s_movk_i32 s74, 0x4000
	s_movk_i32 s75, 0x3000
	v_add_u32_e32 v183, v57, v66
	v_add_u32_e32 v184, v57, v54
	v_add_u32_e32 v185, v61, v56
	s_brev_b32 s62, 60
	s_mov_b32 s82, 0x800000
	v_lshlrev_b32_e32 v88, 1, v50
	s_brev_b32 s83, 36
	v_add_u32_e32 v186, v62, v51
	v_add_u32_e32 v187, v57, v53
	s_mov_b32 s87, s33
	s_mov_b64 s[98:99], 0
	v_mov_b32_e32 v214, v79
	v_mov_b32_e32 v215, v75
	s_branch .LBB0_571

.LBB0_571:
	v_cndmask_b32_e64 v31, v31, 0, s[98:99]
	v_cndmask_b32_e64 v30, v30, 0, s[98:99]
	v_cndmask_b32_e64 v29, v29, 0, s[98:99]
	v_cndmask_b32_e64 v28, v28, 0, s[98:99]
	v_cndmask_b32_e64 v35, v35, 0, s[98:99]
	v_cndmask_b32_e64 v34, v34, 0, s[98:99]
	v_cndmask_b32_e64 v33, v33, 0, s[98:99]
	v_cndmask_b32_e64 v32, v32, 0, s[98:99]
	v_cndmask_b32_e64 v39, v39, 0, s[98:99]
	v_cndmask_b32_e64 v38, v38, 0, s[98:99]
	v_cndmask_b32_e64 v37, v37, 0, s[98:99]
	v_cndmask_b32_e64 v36, v36, 0, s[98:99]
	v_cndmask_b32_e64 v43, v43, 0, s[98:99]
	v_cndmask_b32_e64 v42, v42, 0, s[98:99]
	v_cndmask_b32_e64 v41, v41, 0, s[98:99]
	v_cndmask_b32_e64 v40, v40, 0, s[98:99]
	v_cndmask_b32_e64 v75, v215, 0, s[98:99]
	v_cndmask_b32_e64 v79, v214, 0, s[98:99]
	s_and_saveexec_b64 s[0:1], s[2:3]
	s_cbranch_execz .LBB0_573
	s_waitcnt vmcnt(0)
	ds_bpermute_b32 v44, v172, v73
	v_max_f32_e32 v48, v79, v79
	ds_write_b32 v116, v89
	ds_write_b32 v117, v89
	s_waitcnt lgkmcnt(0)
	v_add_f32_e32 v44, v73, v44
	v_cndmask_b32_e64 v44, v44, v73, s[4:5]
	ds_bpermute_b32 v45, v173, v44
	s_waitcnt lgkmcnt(0)
	v_add_f32_e32 v45, v44, v45
	v_cndmask_b32_e64 v44, v45, v44, s[6:7]
	ds_bpermute_b32 v45, v174, v44
	s_waitcnt lgkmcnt(0)
	v_add_f32_e32 v45, v44, v45
	v_cndmask_b32_e64 v44, v45, v44, s[8:9]
	ds_bpermute_b32 v45, v175, v44
	s_waitcnt lgkmcnt(0)
	v_add_f32_e32 v45, v44, v45
	v_cndmask_b32_e64 v44, v45, v44, s[10:11]
	ds_bpermute_b32 v45, v176, v44
	s_waitcnt lgkmcnt(0)
	v_add_f32_e32 v45, v44, v45
	v_cndmask_b32_e64 v44, v45, v44, s[12:13]
	ds_bpermute_b32 v45, v177, v44
	s_waitcnt lgkmcnt(0)
	v_add_f32_e32 v45, v44, v45
	v_cndmask_b32_e64 v44, v45, v44, s[14:15]
	v_sub_f32_e32 v45, v85, v44
	ds_bpermute_b32 v46, v172, v45
	s_waitcnt lgkmcnt(0)
	v_max_f32_e32 v46, v46, v46
	v_max_f32_e32 v46, v45, v46
	v_cndmask_b32_e64 v46, v46, v45, s[4:5]
	ds_bpermute_b32 v47, v173, v46
	s_waitcnt lgkmcnt(0)
	v_max_f32_e32 v47, v47, v47
	v_max_f32_e32 v47, v46, v47
	v_cndmask_b32_e64 v46, v47, v46, s[6:7]
	ds_bpermute_b32 v47, v174, v46
	s_waitcnt lgkmcnt(0)
	v_max_f32_e32 v47, v47, v47
	v_max_f32_e32 v47, v46, v47
	v_cndmask_b32_e64 v46, v47, v46, s[8:9]
	ds_bpermute_b32 v47, v175, v46
	s_waitcnt lgkmcnt(0)
	v_max_f32_e32 v47, v47, v47
	v_max_f32_e32 v47, v46, v47
	v_cndmask_b32_e64 v46, v47, v46, s[10:11]
	ds_bpermute_b32 v47, v176, v46
	s_waitcnt lgkmcnt(0)
	v_max_f32_e32 v47, v47, v47
	v_max_f32_e32 v47, v46, v47
	v_cndmask_b32_e64 v46, v47, v46, s[12:13]
	ds_bpermute_b32 v47, v177, v46
	v_max_f32_e32 v49, v46, v46
	s_waitcnt lgkmcnt(0)
	v_max_f32_e32 v47, v47, v47
	v_max_f32_e32 v47, v49, v47
	v_cndmask_b32_e64 v46, v47, v46, s[14:15]
	v_max_f32_e32 v46, v46, v46
	v_max_f32_e32 v46, v48, v46
	v_sub_f32_e32 v47, v79, v46
	v_add_f32_e32 v44, v44, v46
	v_mul_f32_e32 v47, 0x3fb8aa3b, v47
	v_mul_f32_e32 v44, 0xbfb8aa3b, v44
	v_exp_f32_e32 v47, v47
	v_exp_f32_e32 v44, v44
	ds_write_b32 v112, v45
	ds_write_b32 v113, v46
	ds_write_b32 v114, v47
	ds_write_b32 v115, v44
	ds_write_b32 v118, v89
.LBB0_573:
	s_or_b64 exec, exec, s[0:1]
	ds_write_b128 v127, v[0:3]
	ds_write_b128 v127, v[4:7] offset:17408
	ds_write_b16 v130, v8 offset:34816
	ds_write_b16_d16_hi v131, v8 offset:34960
	ds_write_b16 v130, v9 offset:35104
	ds_write_b16_d16_hi v131, v9 offset:35248
	ds_write_b16 v130, v10 offset:35392
	ds_write_b16_d16_hi v131, v10 offset:35536
	ds_write_b16 v130, v11 offset:35680
	ds_write_b16_d16_hi v131, v11 offset:35824
	ds_write_b128 v132, v[12:15]
	ds_write_b128 v132, v[16:19] offset:17408
	ds_write_b16 v133, v20 offset:34816
	ds_write_b16_d16_hi v134, v20 offset:34960
	ds_write_b16 v133, v21 offset:35104
	ds_write_b16_d16_hi v134, v21 offset:35248
	ds_write_b16 v133, v22 offset:35392
	ds_write_b16_d16_hi v134, v22 offset:35536
	ds_write_b16 v133, v23 offset:35680
	ds_write_b16_d16_hi v134, v23 offset:35824
	ds_write_b128 v135, v[28:31]
	ds_write_b128 v181, v[32:35] offset:53248
	ds_write_b128 v135, v[36:39] offset:17408
	ds_write_b128 v182, v[40:43] offset:53248
	s_and_saveexec_b64 s[0:1], s[16:17]
	ds_write_b32 v119, v75
	s_or_b64 exec, exec, s[0:1]
	s_add_i32 s86, s87, s84
	s_cmpk_gt_i32 s86, 0xfff
	s_cselect_b64 s[64:65], -1, 0
	s_waitcnt vmcnt(0)
	v_mov_b64_e32 v[46:47], v[26:27]
	s_and_b64 vcc, exec, s[64:65]
	v_mov_b64_e32 v[102:103], v[100:101]
	v_mov_b64_e32 v[104:105], v[98:99]
	v_mov_b64_e32 v[106:107], v[90:91]
	v_mov_b64_e32 v[108:109], v[86:87]
	v_mov_b64_e32 v[44:45], v[24:25]
	s_waitcnt lgkmcnt(0)
	s_barrier
	s_cbranch_vccnz .LBB0_579
	s_and_b32 s43, s86, 0xff
	s_add_i32 s0, s68, s63
	s_and_b32 s0, s0, 0xffffc000
	s_lshl_b32 s1, s43, 6
	s_or_b32 s89, s0, s1
	s_bfe_u32 s88, s86, 0x30008
	v_or_b32_e32 v0, s89, v129
	v_mov_b64_e32 v[44:45], s[52:53]
	v_mad_i64_i32 v[0:1], s[0:1], v0, s71, v[44:45]
	s_lshl_b32 s54, s88, 8
	v_mov_b32_e32 v77, v89
	v_lshl_add_u64 v[0:1], v[0:1], 0, s[54:55]
	v_add_u32_e32 v10, s89, v111
	v_lshl_add_u64 v[0:1], v[0:1], 0, v[76:77]
	v_mad_i64_i32 v[10:11], s[0:1], v10, s71, v[44:45]
	s_cmp_lg_u32 s43, 0
	v_add_co_u32_e32 v2, vcc, s72, v0
	s_cselect_b64 s[0:1], -1, 0
	s_nop 0
	v_addc_co_u32_e32 v3, vcc, 0, v1, vcc
	s_cmp_lg_u64 s[0:1], 0
	v_add_co_u32_e32 v8, vcc, s73, v0
	v_lshl_add_u64 v[10:11], v[10:11], 0, s[54:55]
	s_subb_u32 s42, s86, 0
	v_addc_co_u32_e32 v9, vcc, 0, v1, vcc
	v_lshl_add_u64 v[16:17], v[10:11], 0, v[76:77]
	s_cmp_eq_u32 s43, 0
	v_add_co_u32_e32 v12, vcc, s72, v16
	s_cselect_b64 s[0:1], -1, 0
	s_ashr_i32 s43, s42, 31
	v_addc_co_u32_e32 v13, vcc, 0, v17, vcc
	s_lshl_b64 s[90:91], s[42:43], 15
	v_add_co_u32_e32 v20, vcc, s73, v16
	v_lshl_add_u64 v[36:37], v[92:93], 0, s[90:91]
	v_mov_b32_e32 v81, v89
	v_mov_b32_e32 v83, v89
	v_addc_co_u32_e32 v21, vcc, 0, v17, vcc
	v_lshl_add_u64 v[38:39], v[36:37], 0, v[80:81]
	v_lshl_add_u64 v[32:33], v[36:37], 0, v[82:83]
	s_lshl_b64 s[90:91], s[42:43], 9
	s_lshl_b64 s[42:43], s[42:43], 2
	global_load_dwordx4 v[0:3], v[2:3], off offset:2048
	s_nop 0
	global_load_dwordx4 v[4:7], v[8:9], off
	s_nop 0
	global_load_dwordx4 v[8:11], v[8:9], off offset:2048
	s_nop 0
	global_load_dwordx4 v[12:15], v[12:13], off offset:2048
	s_nop 0
	global_load_dwordx4 v[16:19], v[20:21], off
	s_nop 0
	global_load_dwordx4 v[20:23], v[20:21], off offset:2048
	s_nop 0
	global_load_dwordx4 v[28:31], v[38:39], off
	s_nop 0
	global_load_dwordx4 v[32:35], v[32:33], off
	v_add_co_u32_e32 v38, vcc, s74, v38
	v_mov_b32_e32 v79, v89
	s_add_u32 s42, s66, s42
	v_addc_co_u32_e32 v39, vcc, 0, v39, vcc
	v_lshl_add_u64 v[40:41], v[36:37], 0, v[78:79]
	s_addc_u32 s43, s67, s43
	v_or_b32_e32 v56, s89, v110
	global_load_dwordx4 v[36:39], v[38:39], off
	s_nop 0
	global_load_dwordx4 v[40:43], v[40:41], off
	v_mov_b32_e32 v73, v89
	global_load_dword v214, v89, s[42:43]
	v_mad_i64_i32 v[50:51], s[42:43], v56, s71, v[44:45]
	v_lshl_add_u64 v[50:51], v[50:51], 0, s[54:55]
	v_or_b32_e32 v49, 16, v56
	v_lshl_add_u64 v[50:51], v[50:51], 0, v[72:73]
	v_mov_b32_e32 v75, v89
	v_mad_i64_i32 v[52:53], s[42:43], v49, s71, v[44:45]
	v_lshl_add_u64 v[50:51], v[50:51], 0, v[74:75]
	v_lshl_add_u64 v[52:53], v[52:53], 0, s[54:55]
	v_or_b32_e32 v49, 32, v56
	v_add_co_u32_e32 v50, vcc, s75, v50
	v_lshl_add_u64 v[52:53], v[52:53], 0, v[72:73]
	v_mad_i64_i32 v[54:55], s[42:43], v49, s71, v[44:45]
	v_addc_co_u32_e32 v51, vcc, 0, v51, vcc
	v_lshl_add_u64 v[52:53], v[52:53], 0, v[74:75]
	v_lshl_add_u64 v[54:55], v[54:55], 0, s[54:55]
	v_add_co_u32_e32 v52, vcc, s75, v52
	v_lshl_add_u64 v[54:55], v[54:55], 0, v[72:73]
	s_nop 0
	v_addc_co_u32_e32 v53, vcc, 0, v53, vcc
	v_lshl_add_u64 v[54:55], v[54:55], 0, v[74:75]
	v_lshl_add_u64 v[46:47], v[96:97], 0, s[90:91]
	v_add_co_u32_e32 v54, vcc, s75, v54
	v_mov_b32_e32 v85, 0
	s_nop 0
	v_addc_co_u32_e32 v55, vcc, 0, v55, vcc
	global_load_dword v215, v[46:47], off
	global_load_dwordx2 v[102:103], v[50:51], off
	global_load_dwordx2 v[104:105], v[52:53], off
	global_load_dwordx2 v[106:107], v[54:55], off
	v_or_b32_e32 v46, 48, v56
	v_mad_i64_i32 v[44:45], s[42:43], v46, s71, v[44:45]
	v_lshl_add_u64 v[44:45], v[44:45], 0, s[54:55]
	v_lshl_add_u64 v[44:45], v[44:45], 0, v[72:73]
	v_lshl_add_u64 v[44:45], v[44:45], 0, v[74:75]
	v_add_co_u32_e32 v44, vcc, 0x3000, v44
	s_lshl_b32 s54, s88, 9
	s_nop 0
	v_addc_co_u32_e32 v45, vcc, 0, v45, vcc
	global_load_dwordx2 v[108:109], v[44:45], off
	v_lshl_add_u64 v[44:45], v[94:95], 0, s[54:55]
	global_load_dwordx4 v[44:47], v[44:45], off
	v_mov_b32_e32 v73, 0
	s_and_saveexec_b64 s[42:43], s[2:3]
	s_cbranch_execz .LBB0_578
	v_or_b32_e32 v50, s89, v128
	v_ashrrev_i32_e32 v51, 31, v50
	v_lshlrev_b64 v[50:51], 6, v[50:51]
	v_lshl_add_u64 v[50:51], s[50:51], 0, v[50:51]
	s_lshl_b32 s54, s88, 2
	v_lshl_add_u64 v[50:51], v[50:51], 0, s[54:55]
	global_load_dword v85, v[50:51], off
	global_load_dword v73, v[50:51], off offset:32
.LBB0_578:
	s_or_b64 exec, exec, s[42:43]
	s_mov_b64 s[98:99], s[0:1]
